# FFN-up LN-fix vector staging loop unrolled: 22 loads in flight instead of 11 serialized round trips
# speedup vs baseline: 1.0187x; 1.0039x over previous
; __device__ __forceinline__ unsigned cvt_pk_bf16(float lo, float hi) { unsigned r; asm volatile("v_cvt_pk_bf16_f32 %0, %1, %2" : "=v"(r) : "v"(lo), "v"(hi)); return r; }
; #define LAS __attribute__((address_space(3)))
; __global__ void __launch_bounds__(512, 2) mega_fwd(Params P) {
;     ...
;                   { LAS unsigned* CV = (LAS unsigned*)(lds + 131072); for (int i = tid; i < 5632; i += 512) CV[i] = (cvt_pk_bf16(cvk[i], 0.f) & 0xffffu) | (cvt_pk_bf16(cvk[5632 + i], 0.f) << 16);
.LBB0_881:
	v_add_co_u32_e32 v6, vcc, 0xffffa800, v4
	s_nop 1
	v_addc_co_u32_e32 v7, vcc, -1, v5, vcc
	global_load_dword v8, v[6:7], off
	global_load_dword v9, v[4:5], off
	v_lshl_add_u64 v[4:5], v[4:5], 0, s[42:43]
	v_add_co_u32_e32 v6, vcc, 0xffffa800, v4
	s_nop 1
	v_addc_co_u32_e32 v7, vcc, -1, v5, vcc
	global_load_dword v10, v[6:7], off
	global_load_dword v11, v[4:5], off
	v_lshl_add_u64 v[4:5], v[4:5], 0, s[42:43]
	v_add_co_u32_e32 v6, vcc, 0xffffa800, v4
	s_nop 1
	v_addc_co_u32_e32 v7, vcc, -1, v5, vcc
	global_load_dword v12, v[6:7], off
	global_load_dword v13, v[4:5], off
	v_lshl_add_u64 v[4:5], v[4:5], 0, s[42:43]
	v_add_co_u32_e32 v6, vcc, 0xffffa800, v4
	s_nop 1
	v_addc_co_u32_e32 v7, vcc, -1, v5, vcc
	global_load_dword v14, v[6:7], off
	global_load_dword v15, v[4:5], off
	v_lshl_add_u64 v[4:5], v[4:5], 0, s[42:43]
	v_add_co_u32_e32 v6, vcc, 0xffffa800, v4
	s_nop 1
	v_addc_co_u32_e32 v7, vcc, -1, v5, vcc
	global_load_dword v16, v[6:7], off
	global_load_dword v17, v[4:5], off
	v_lshl_add_u64 v[4:5], v[4:5], 0, s[42:43]
	v_add_co_u32_e32 v6, vcc, 0xffffa800, v4
	s_nop 1
	v_addc_co_u32_e32 v7, vcc, -1, v5, vcc
	global_load_dword v18, v[6:7], off
	global_load_dword v19, v[4:5], off
	v_lshl_add_u64 v[4:5], v[4:5], 0, s[42:43]
	v_add_co_u32_e32 v6, vcc, 0xffffa800, v4
	s_nop 1
	v_addc_co_u32_e32 v7, vcc, -1, v5, vcc
	global_load_dword v20, v[6:7], off
	global_load_dword v21, v[4:5], off
	v_lshl_add_u64 v[4:5], v[4:5], 0, s[42:43]
	v_add_co_u32_e32 v6, vcc, 0xffffa800, v4
	s_nop 1
	v_addc_co_u32_e32 v7, vcc, -1, v5, vcc
	global_load_dword v22, v[6:7], off
	global_load_dword v23, v[4:5], off
	v_lshl_add_u64 v[4:5], v[4:5], 0, s[42:43]
	v_add_co_u32_e32 v6, vcc, 0xffffa800, v4
	s_nop 1
	v_addc_co_u32_e32 v7, vcc, -1, v5, vcc
	global_load_dword v24, v[6:7], off
	global_load_dword v25, v[4:5], off
	v_lshl_add_u64 v[4:5], v[4:5], 0, s[42:43]
	v_add_co_u32_e32 v6, vcc, 0xffffa800, v4
	s_nop 1
	v_addc_co_u32_e32 v7, vcc, -1, v5, vcc
	global_load_dword v26, v[6:7], off
	global_load_dword v27, v[4:5], off
	v_lshl_add_u64 v[4:5], v[4:5], 0, s[42:43]
	v_add_co_u32_e32 v6, vcc, 0xffffa800, v4
	s_nop 1
	v_addc_co_u32_e32 v7, vcc, -1, v5, vcc
	global_load_dword v28, v[6:7], off
	global_load_dword v29, v[4:5], off
	s_waitcnt vmcnt(0) lgkmcnt(0)
	v_cvt_pk_bf16_f32 v8, v8, v1
	v_cvt_pk_bf16_f32 v9, v9, v1
	v_and_b32_e32 v8, 0xffff, v8
	v_lshl_or_b32 v8, v9, 16, v8
	ds_write_b32 v3, v8
	v_cvt_pk_bf16_f32 v10, v10, v1
	v_cvt_pk_bf16_f32 v11, v11, v1
	v_and_b32_e32 v10, 0xffff, v10
	v_lshl_or_b32 v10, v11, 16, v10
	ds_write_b32 v3, v10 offset:2048
	v_cvt_pk_bf16_f32 v12, v12, v1
	v_cvt_pk_bf16_f32 v13, v13, v1
	v_and_b32_e32 v12, 0xffff, v12
	v_lshl_or_b32 v12, v13, 16, v12
	ds_write_b32 v3, v12 offset:4096
	v_cvt_pk_bf16_f32 v14, v14, v1
	v_cvt_pk_bf16_f32 v15, v15, v1
	v_and_b32_e32 v14, 0xffff, v14
	v_lshl_or_b32 v14, v15, 16, v14
	ds_write_b32 v3, v14 offset:6144
	v_cvt_pk_bf16_f32 v16, v16, v1
	v_cvt_pk_bf16_f32 v17, v17, v1
	v_and_b32_e32 v16, 0xffff, v16
	v_lshl_or_b32 v16, v17, 16, v16
	ds_write_b32 v3, v16 offset:8192
	v_cvt_pk_bf16_f32 v18, v18, v1
	v_cvt_pk_bf16_f32 v19, v19, v1
	v_and_b32_e32 v18, 0xffff, v18
	v_lshl_or_b32 v18, v19, 16, v18
	ds_write_b32 v3, v18 offset:10240
	v_cvt_pk_bf16_f32 v20, v20, v1
	v_cvt_pk_bf16_f32 v21, v21, v1
	v_and_b32_e32 v20, 0xffff, v20
	v_lshl_or_b32 v20, v21, 16, v20
	ds_write_b32 v3, v20 offset:12288
	v_cvt_pk_bf16_f32 v22, v22, v1
	v_cvt_pk_bf16_f32 v23, v23, v1
	v_and_b32_e32 v22, 0xffff, v22
	v_lshl_or_b32 v22, v23, 16, v22
	ds_write_b32 v3, v22 offset:14336
	v_cvt_pk_bf16_f32 v24, v24, v1
	v_cvt_pk_bf16_f32 v25, v25, v1
	v_and_b32_e32 v24, 0xffff, v24
	v_lshl_or_b32 v24, v25, 16, v24
	ds_write_b32 v3, v24 offset:16384
	v_cvt_pk_bf16_f32 v26, v26, v1
	v_cvt_pk_bf16_f32 v27, v27, v1
	v_and_b32_e32 v26, 0xffff, v26
	v_lshl_or_b32 v26, v27, 16, v26
	ds_write_b32 v3, v26 offset:18432
	v_cvt_pk_bf16_f32 v28, v28, v1
	v_cvt_pk_bf16_f32 v29, v29, v1
	v_and_b32_e32 v28, 0xffff, v28
	v_lshl_or_b32 v28, v29, 16, v28
	ds_write_b32 v3, v28 offset:20480
